# final rmsnorm: each store instruction now writes 1 KiB of consecutive output bytes (lane owns 4 consecutive columns of 4 row quarters) instead of 16 B at a 32 B stride
# speedup vs baseline: 1.0235x; 1.0078x over previous
.LBB0_946:
	v_readfirstlane_b32 s4, v226
	s_lshr_b32 s4, s4, 6
	s_lshl_b32 s5, s2, 3
	s_add_i32 s14, s4, s5
	s_lshl_b32 s38, s78, 3
	v_readlane_b32 s48, v253, 0
	v_readlane_b32 s49, v253, 1
	v_readlane_b32 s50, v253, 2
	v_readlane_b32 s51, v253, 3
	v_readlane_b32 s54, v253, 24
	v_readlane_b32 s55, v253, 25
	s_add_u32 s52, s50, 0x342000
	s_addc_u32 s53, s51, 0
	v_lshlrev_b32_e32 v4, 4, v227
	v_lshlrev_b32_e32 v5, 3, v227
	v_mov_b32_e32 v24, 0x358637bd
	global_load_dwordx4 v[8:11], v4, s[54:55]
	global_load_dwordx4 v[12:15], v4, s[54:55] offset:1024
	global_load_dwordx4 v[16:19], v4, s[54:55] offset:2048
	global_load_dwordx4 v[20:23], v4, s[54:55] offset:3072
.Lfn_loop:
	s_cmpk_lt_i32 s14, 0x4200
	s_cbranch_scc0 .LBB0_955
	s_mul_i32 s15, s38, 7
	s_add_i32 s15, s15, s14
	s_cmpk_lt_i32 s15, 0x4200
	s_cbranch_scc0 .Lfn_try4
	s_mov_b32 s58, s14
	s_lshl_b32 s59, s58, 11
	s_add_u32 s56, s46, s59
	s_addc_u32 s57, s47, 0
	s_lshl_b32 s59, s58, 2
	s_load_dword s60, s[52:53], s59
	global_load_dwordx2 v[32:33], v5, s[56:57]
	global_load_dwordx2 v[34:35], v5, s[56:57] offset:512
	global_load_dwordx2 v[36:37], v5, s[56:57] offset:1024
	global_load_dwordx2 v[38:39], v5, s[56:57] offset:1536
	s_add_i32 s58, s58, s38
	s_lshl_b32 s59, s58, 11
	s_add_u32 s56, s46, s59
	s_addc_u32 s57, s47, 0
	s_lshl_b32 s59, s58, 2
	s_load_dword s61, s[52:53], s59
	global_load_dwordx2 v[40:41], v5, s[56:57]
	global_load_dwordx2 v[42:43], v5, s[56:57] offset:512
	global_load_dwordx2 v[44:45], v5, s[56:57] offset:1024
	global_load_dwordx2 v[46:47], v5, s[56:57] offset:1536
	s_add_i32 s58, s58, s38
	s_lshl_b32 s59, s58, 11
	s_add_u32 s56, s46, s59
	s_addc_u32 s57, s47, 0
	s_lshl_b32 s59, s58, 2
	s_load_dword s62, s[52:53], s59
	global_load_dwordx2 v[48:49], v5, s[56:57]
	global_load_dwordx2 v[50:51], v5, s[56:57] offset:512
	global_load_dwordx2 v[52:53], v5, s[56:57] offset:1024
	global_load_dwordx2 v[54:55], v5, s[56:57] offset:1536
	s_add_i32 s58, s58, s38
	s_lshl_b32 s59, s58, 11
	s_add_u32 s56, s46, s59
	s_addc_u32 s57, s47, 0
	s_lshl_b32 s59, s58, 2
	s_load_dword s63, s[52:53], s59
	global_load_dwordx2 v[56:57], v5, s[56:57]
	global_load_dwordx2 v[58:59], v5, s[56:57] offset:512
	global_load_dwordx2 v[60:61], v5, s[56:57] offset:1024
	global_load_dwordx2 v[62:63], v5, s[56:57] offset:1536
	s_add_i32 s58, s58, s38
	s_lshl_b32 s59, s58, 11
	s_add_u32 s56, s46, s59
	s_addc_u32 s57, s47, 0
	s_lshl_b32 s59, s58, 2
	s_load_dword s64, s[52:53], s59
	global_load_dwordx2 v[64:65], v5, s[56:57]
	global_load_dwordx2 v[66:67], v5, s[56:57] offset:512
	global_load_dwordx2 v[68:69], v5, s[56:57] offset:1024
	global_load_dwordx2 v[70:71], v5, s[56:57] offset:1536
	s_add_i32 s58, s58, s38
	s_lshl_b32 s59, s58, 11
	s_add_u32 s56, s46, s59
	s_addc_u32 s57, s47, 0
	s_lshl_b32 s59, s58, 2
	s_load_dword s65, s[52:53], s59
	global_load_dwordx2 v[72:73], v5, s[56:57]
	global_load_dwordx2 v[74:75], v5, s[56:57] offset:512
	global_load_dwordx2 v[76:77], v5, s[56:57] offset:1024
	global_load_dwordx2 v[78:79], v5, s[56:57] offset:1536
	s_add_i32 s58, s58, s38
	s_lshl_b32 s59, s58, 11
	s_add_u32 s56, s46, s59
	s_addc_u32 s57, s47, 0
	s_lshl_b32 s59, s58, 2
	s_load_dword s66, s[52:53], s59
	global_load_dwordx2 v[80:81], v5, s[56:57]
	global_load_dwordx2 v[82:83], v5, s[56:57] offset:512
	global_load_dwordx2 v[84:85], v5, s[56:57] offset:1024
	global_load_dwordx2 v[86:87], v5, s[56:57] offset:1536
	s_add_i32 s58, s58, s38
	s_lshl_b32 s59, s58, 11
	s_add_u32 s56, s46, s59
	s_addc_u32 s57, s47, 0
	s_lshl_b32 s59, s58, 2
	s_load_dword s67, s[52:53], s59
	global_load_dwordx2 v[88:89], v5, s[56:57]
	global_load_dwordx2 v[90:91], v5, s[56:57] offset:512
	global_load_dwordx2 v[92:93], v5, s[56:57] offset:1024
	global_load_dwordx2 v[94:95], v5, s[56:57] offset:1536
	s_waitcnt lgkmcnt(0)
	s_mov_b32 s58, s14
	s_lshl_b32 s59, s58, 12
	s_add_u32 s56, s48, s59
	s_addc_u32 s57, s49, 0
	v_mov_b32_e32 v6, s60
	v_fmamk_f32 v6, v6, 0x3a800000, v24
	v_rsq_f32_e32 v6, v6
	s_waitcnt vmcnt(28)
	v_lshlrev_b32_e32 v96, 16, v32
	v_and_b32_e32 v97, 0xffff0000, v32
	v_lshlrev_b32_e32 v98, 16, v33
	v_and_b32_e32 v99, 0xffff0000, v33
	v_lshlrev_b32_e32 v100, 16, v34
	v_and_b32_e32 v101, 0xffff0000, v34
	v_lshlrev_b32_e32 v102, 16, v35
	v_and_b32_e32 v103, 0xffff0000, v35
	v_lshlrev_b32_e32 v104, 16, v36
	v_and_b32_e32 v105, 0xffff0000, v36
	v_lshlrev_b32_e32 v106, 16, v37
	v_and_b32_e32 v107, 0xffff0000, v37
	v_lshlrev_b32_e32 v108, 16, v38
	v_and_b32_e32 v109, 0xffff0000, v38
	v_lshlrev_b32_e32 v110, 16, v39
	v_and_b32_e32 v111, 0xffff0000, v39
	v_pk_mul_f32 v[96:97], v[6:7], v[96:97] op_sel_hi:[0,1]
	v_pk_mul_f32 v[98:99], v[6:7], v[98:99] op_sel_hi:[0,1]
	v_pk_mul_f32 v[100:101], v[6:7], v[100:101] op_sel_hi:[0,1]
	v_pk_mul_f32 v[102:103], v[6:7], v[102:103] op_sel_hi:[0,1]
	v_pk_mul_f32 v[104:105], v[6:7], v[104:105] op_sel_hi:[0,1]
	v_pk_mul_f32 v[106:107], v[6:7], v[106:107] op_sel_hi:[0,1]
	v_pk_mul_f32 v[108:109], v[6:7], v[108:109] op_sel_hi:[0,1]
	v_pk_mul_f32 v[110:111], v[6:7], v[110:111] op_sel_hi:[0,1]
	v_pk_mul_f32 v[96:97], v[8:9], v[96:97]
	v_pk_mul_f32 v[98:99], v[10:11], v[98:99]
	v_pk_mul_f32 v[100:101], v[12:13], v[100:101]
	v_pk_mul_f32 v[102:103], v[14:15], v[102:103]
	v_pk_mul_f32 v[104:105], v[16:17], v[104:105]
	v_pk_mul_f32 v[106:107], v[18:19], v[106:107]
	v_pk_mul_f32 v[108:109], v[20:21], v[108:109]
	v_pk_mul_f32 v[110:111], v[22:23], v[110:111]
	global_store_dwordx4 v4, v[96:99], s[56:57] nt
	global_store_dwordx4 v4, v[100:103], s[56:57] offset:1024 nt
	global_store_dwordx4 v4, v[104:107], s[56:57] offset:2048 nt
	global_store_dwordx4 v4, v[108:111], s[56:57] offset:3072 nt
	s_add_i32 s58, s58, s38
	s_lshl_b32 s59, s58, 12
	s_add_u32 s56, s48, s59
	s_addc_u32 s57, s49, 0
	v_mov_b32_e32 v6, s61
	v_fmamk_f32 v6, v6, 0x3a800000, v24
	v_rsq_f32_e32 v6, v6
	s_waitcnt vmcnt(28)
	v_lshlrev_b32_e32 v112, 16, v40
	v_and_b32_e32 v113, 0xffff0000, v40
	v_lshlrev_b32_e32 v114, 16, v41
	v_and_b32_e32 v115, 0xffff0000, v41
	v_lshlrev_b32_e32 v116, 16, v42
	v_and_b32_e32 v117, 0xffff0000, v42
	v_lshlrev_b32_e32 v118, 16, v43
	v_and_b32_e32 v119, 0xffff0000, v43
	v_lshlrev_b32_e32 v120, 16, v44
	v_and_b32_e32 v121, 0xffff0000, v44
	v_lshlrev_b32_e32 v122, 16, v45
	v_and_b32_e32 v123, 0xffff0000, v45
	v_lshlrev_b32_e32 v124, 16, v46
	v_and_b32_e32 v125, 0xffff0000, v46
	v_lshlrev_b32_e32 v126, 16, v47
	v_and_b32_e32 v127, 0xffff0000, v47
	v_pk_mul_f32 v[112:113], v[6:7], v[112:113] op_sel_hi:[0,1]
	v_pk_mul_f32 v[114:115], v[6:7], v[114:115] op_sel_hi:[0,1]
	v_pk_mul_f32 v[116:117], v[6:7], v[116:117] op_sel_hi:[0,1]
	v_pk_mul_f32 v[118:119], v[6:7], v[118:119] op_sel_hi:[0,1]
	v_pk_mul_f32 v[120:121], v[6:7], v[120:121] op_sel_hi:[0,1]
	v_pk_mul_f32 v[122:123], v[6:7], v[122:123] op_sel_hi:[0,1]
	v_pk_mul_f32 v[124:125], v[6:7], v[124:125] op_sel_hi:[0,1]
	v_pk_mul_f32 v[126:127], v[6:7], v[126:127] op_sel_hi:[0,1]
	v_pk_mul_f32 v[112:113], v[8:9], v[112:113]
	v_pk_mul_f32 v[114:115], v[10:11], v[114:115]
	v_pk_mul_f32 v[116:117], v[12:13], v[116:117]
	v_pk_mul_f32 v[118:119], v[14:15], v[118:119]
	v_pk_mul_f32 v[120:121], v[16:17], v[120:121]
	v_pk_mul_f32 v[122:123], v[18:19], v[122:123]
	v_pk_mul_f32 v[124:125], v[20:21], v[124:125]
	v_pk_mul_f32 v[126:127], v[22:23], v[126:127]
	global_store_dwordx4 v4, v[112:115], s[56:57] nt
	global_store_dwordx4 v4, v[116:119], s[56:57] offset:1024 nt
	global_store_dwordx4 v4, v[120:123], s[56:57] offset:2048 nt
	global_store_dwordx4 v4, v[124:127], s[56:57] offset:3072 nt
	s_add_i32 s58, s58, s38
	s_lshl_b32 s59, s58, 12
	s_add_u32 s56, s48, s59
	s_addc_u32 s57, s49, 0
	v_mov_b32_e32 v6, s62
	v_fmamk_f32 v6, v6, 0x3a800000, v24
	v_rsq_f32_e32 v6, v6
	s_waitcnt vmcnt(28)
	v_lshlrev_b32_e32 v128, 16, v48
	v_and_b32_e32 v129, 0xffff0000, v48
	v_lshlrev_b32_e32 v130, 16, v49
	v_and_b32_e32 v131, 0xffff0000, v49
	v_lshlrev_b32_e32 v132, 16, v50
	v_and_b32_e32 v133, 0xffff0000, v50
	v_lshlrev_b32_e32 v134, 16, v51
	v_and_b32_e32 v135, 0xffff0000, v51
	v_lshlrev_b32_e32 v136, 16, v52
	v_and_b32_e32 v137, 0xffff0000, v52
	v_lshlrev_b32_e32 v138, 16, v53
	v_and_b32_e32 v139, 0xffff0000, v53
	v_lshlrev_b32_e32 v140, 16, v54
	v_and_b32_e32 v141, 0xffff0000, v54
	v_lshlrev_b32_e32 v142, 16, v55
	v_and_b32_e32 v143, 0xffff0000, v55
	v_pk_mul_f32 v[128:129], v[6:7], v[128:129] op_sel_hi:[0,1]
	v_pk_mul_f32 v[130:131], v[6:7], v[130:131] op_sel_hi:[0,1]
	v_pk_mul_f32 v[132:133], v[6:7], v[132:133] op_sel_hi:[0,1]
	v_pk_mul_f32 v[134:135], v[6:7], v[134:135] op_sel_hi:[0,1]
	v_pk_mul_f32 v[136:137], v[6:7], v[136:137] op_sel_hi:[0,1]
	v_pk_mul_f32 v[138:139], v[6:7], v[138:139] op_sel_hi:[0,1]
	v_pk_mul_f32 v[140:141], v[6:7], v[140:141] op_sel_hi:[0,1]
	v_pk_mul_f32 v[142:143], v[6:7], v[142:143] op_sel_hi:[0,1]
	v_pk_mul_f32 v[128:129], v[8:9], v[128:129]
	v_pk_mul_f32 v[130:131], v[10:11], v[130:131]
	v_pk_mul_f32 v[132:133], v[12:13], v[132:133]
	v_pk_mul_f32 v[134:135], v[14:15], v[134:135]
	v_pk_mul_f32 v[136:137], v[16:17], v[136:137]
	v_pk_mul_f32 v[138:139], v[18:19], v[138:139]
	v_pk_mul_f32 v[140:141], v[20:21], v[140:141]
	v_pk_mul_f32 v[142:143], v[22:23], v[142:143]
	global_store_dwordx4 v4, v[128:131], s[56:57] nt
	global_store_dwordx4 v4, v[132:135], s[56:57] offset:1024 nt
	global_store_dwordx4 v4, v[136:139], s[56:57] offset:2048 nt
	global_store_dwordx4 v4, v[140:143], s[56:57] offset:3072 nt
	s_add_i32 s58, s58, s38
	s_lshl_b32 s59, s58, 12
	s_add_u32 s56, s48, s59
	s_addc_u32 s57, s49, 0
	v_mov_b32_e32 v6, s63
	v_fmamk_f32 v6, v6, 0x3a800000, v24
	v_rsq_f32_e32 v6, v6
	s_waitcnt vmcnt(28)
	v_lshlrev_b32_e32 v144, 16, v56
	v_and_b32_e32 v145, 0xffff0000, v56
	v_lshlrev_b32_e32 v146, 16, v57
	v_and_b32_e32 v147, 0xffff0000, v57
	v_lshlrev_b32_e32 v148, 16, v58
	v_and_b32_e32 v149, 0xffff0000, v58
	v_lshlrev_b32_e32 v150, 16, v59
	v_and_b32_e32 v151, 0xffff0000, v59
	v_lshlrev_b32_e32 v152, 16, v60
	v_and_b32_e32 v153, 0xffff0000, v60
	v_lshlrev_b32_e32 v154, 16, v61
	v_and_b32_e32 v155, 0xffff0000, v61
	v_lshlrev_b32_e32 v156, 16, v62
	v_and_b32_e32 v157, 0xffff0000, v62
	v_lshlrev_b32_e32 v158, 16, v63
	v_and_b32_e32 v159, 0xffff0000, v63
	v_pk_mul_f32 v[144:145], v[6:7], v[144:145] op_sel_hi:[0,1]
	v_pk_mul_f32 v[146:147], v[6:7], v[146:147] op_sel_hi:[0,1]
	v_pk_mul_f32 v[148:149], v[6:7], v[148:149] op_sel_hi:[0,1]
	v_pk_mul_f32 v[150:151], v[6:7], v[150:151] op_sel_hi:[0,1]
	v_pk_mul_f32 v[152:153], v[6:7], v[152:153] op_sel_hi:[0,1]
	v_pk_mul_f32 v[154:155], v[6:7], v[154:155] op_sel_hi:[0,1]
	v_pk_mul_f32 v[156:157], v[6:7], v[156:157] op_sel_hi:[0,1]
	v_pk_mul_f32 v[158:159], v[6:7], v[158:159] op_sel_hi:[0,1]
	v_pk_mul_f32 v[144:145], v[8:9], v[144:145]
	v_pk_mul_f32 v[146:147], v[10:11], v[146:147]
	v_pk_mul_f32 v[148:149], v[12:13], v[148:149]
	v_pk_mul_f32 v[150:151], v[14:15], v[150:151]
	v_pk_mul_f32 v[152:153], v[16:17], v[152:153]
	v_pk_mul_f32 v[154:155], v[18:19], v[154:155]
	v_pk_mul_f32 v[156:157], v[20:21], v[156:157]
	v_pk_mul_f32 v[158:159], v[22:23], v[158:159]
	global_store_dwordx4 v4, v[144:147], s[56:57] nt
	global_store_dwordx4 v4, v[148:151], s[56:57] offset:1024 nt
	global_store_dwordx4 v4, v[152:155], s[56:57] offset:2048 nt
	global_store_dwordx4 v4, v[156:159], s[56:57] offset:3072 nt
	s_add_i32 s58, s58, s38
	s_lshl_b32 s59, s58, 12
	s_add_u32 s56, s48, s59
	s_addc_u32 s57, s49, 0
	v_mov_b32_e32 v6, s64
	v_fmamk_f32 v6, v6, 0x3a800000, v24
	v_rsq_f32_e32 v6, v6
	s_waitcnt vmcnt(28)
	v_lshlrev_b32_e32 v160, 16, v64
	v_and_b32_e32 v161, 0xffff0000, v64
	v_lshlrev_b32_e32 v162, 16, v65
	v_and_b32_e32 v163, 0xffff0000, v65
	v_lshlrev_b32_e32 v164, 16, v66
	v_and_b32_e32 v165, 0xffff0000, v66
	v_lshlrev_b32_e32 v166, 16, v67
	v_and_b32_e32 v167, 0xffff0000, v67
	v_lshlrev_b32_e32 v168, 16, v68
	v_and_b32_e32 v169, 0xffff0000, v68
	v_lshlrev_b32_e32 v170, 16, v69
	v_and_b32_e32 v171, 0xffff0000, v69
	v_lshlrev_b32_e32 v172, 16, v70
	v_and_b32_e32 v173, 0xffff0000, v70
	v_lshlrev_b32_e32 v174, 16, v71
	v_and_b32_e32 v175, 0xffff0000, v71
	v_pk_mul_f32 v[160:161], v[6:7], v[160:161] op_sel_hi:[0,1]
	v_pk_mul_f32 v[162:163], v[6:7], v[162:163] op_sel_hi:[0,1]
	v_pk_mul_f32 v[164:165], v[6:7], v[164:165] op_sel_hi:[0,1]
	v_pk_mul_f32 v[166:167], v[6:7], v[166:167] op_sel_hi:[0,1]
	v_pk_mul_f32 v[168:169], v[6:7], v[168:169] op_sel_hi:[0,1]
	v_pk_mul_f32 v[170:171], v[6:7], v[170:171] op_sel_hi:[0,1]
	v_pk_mul_f32 v[172:173], v[6:7], v[172:173] op_sel_hi:[0,1]
	v_pk_mul_f32 v[174:175], v[6:7], v[174:175] op_sel_hi:[0,1]
	v_pk_mul_f32 v[160:161], v[8:9], v[160:161]
	v_pk_mul_f32 v[162:163], v[10:11], v[162:163]
	v_pk_mul_f32 v[164:165], v[12:13], v[164:165]
	v_pk_mul_f32 v[166:167], v[14:15], v[166:167]
	v_pk_mul_f32 v[168:169], v[16:17], v[168:169]
	v_pk_mul_f32 v[170:171], v[18:19], v[170:171]
	v_pk_mul_f32 v[172:173], v[20:21], v[172:173]
	v_pk_mul_f32 v[174:175], v[22:23], v[174:175]
	global_store_dwordx4 v4, v[160:163], s[56:57] nt
	global_store_dwordx4 v4, v[164:167], s[56:57] offset:1024 nt
	global_store_dwordx4 v4, v[168:171], s[56:57] offset:2048 nt
	global_store_dwordx4 v4, v[172:175], s[56:57] offset:3072 nt
	s_add_i32 s58, s58, s38
	s_lshl_b32 s59, s58, 12
	s_add_u32 s56, s48, s59
	s_addc_u32 s57, s49, 0
	v_mov_b32_e32 v6, s65
	v_fmamk_f32 v6, v6, 0x3a800000, v24
	v_rsq_f32_e32 v6, v6
	s_waitcnt vmcnt(28)
	v_lshlrev_b32_e32 v176, 16, v72
	v_and_b32_e32 v177, 0xffff0000, v72
	v_lshlrev_b32_e32 v178, 16, v73
	v_and_b32_e32 v179, 0xffff0000, v73
	v_lshlrev_b32_e32 v180, 16, v74
	v_and_b32_e32 v181, 0xffff0000, v74
	v_lshlrev_b32_e32 v182, 16, v75
	v_and_b32_e32 v183, 0xffff0000, v75
	v_lshlrev_b32_e32 v184, 16, v76
	v_and_b32_e32 v185, 0xffff0000, v76
	v_lshlrev_b32_e32 v186, 16, v77
	v_and_b32_e32 v187, 0xffff0000, v77
	v_lshlrev_b32_e32 v188, 16, v78
	v_and_b32_e32 v189, 0xffff0000, v78
	v_lshlrev_b32_e32 v190, 16, v79
	v_and_b32_e32 v191, 0xffff0000, v79
	v_pk_mul_f32 v[176:177], v[6:7], v[176:177] op_sel_hi:[0,1]
	v_pk_mul_f32 v[178:179], v[6:7], v[178:179] op_sel_hi:[0,1]
	v_pk_mul_f32 v[180:181], v[6:7], v[180:181] op_sel_hi:[0,1]
	v_pk_mul_f32 v[182:183], v[6:7], v[182:183] op_sel_hi:[0,1]
	v_pk_mul_f32 v[184:185], v[6:7], v[184:185] op_sel_hi:[0,1]
	v_pk_mul_f32 v[186:187], v[6:7], v[186:187] op_sel_hi:[0,1]
	v_pk_mul_f32 v[188:189], v[6:7], v[188:189] op_sel_hi:[0,1]
	v_pk_mul_f32 v[190:191], v[6:7], v[190:191] op_sel_hi:[0,1]
	v_pk_mul_f32 v[176:177], v[8:9], v[176:177]
	v_pk_mul_f32 v[178:179], v[10:11], v[178:179]
	v_pk_mul_f32 v[180:181], v[12:13], v[180:181]
	v_pk_mul_f32 v[182:183], v[14:15], v[182:183]
	v_pk_mul_f32 v[184:185], v[16:17], v[184:185]
	v_pk_mul_f32 v[186:187], v[18:19], v[186:187]
	v_pk_mul_f32 v[188:189], v[20:21], v[188:189]
	v_pk_mul_f32 v[190:191], v[22:23], v[190:191]
	global_store_dwordx4 v4, v[176:179], s[56:57] nt
	global_store_dwordx4 v4, v[180:183], s[56:57] offset:1024 nt
	global_store_dwordx4 v4, v[184:187], s[56:57] offset:2048 nt
	global_store_dwordx4 v4, v[188:191], s[56:57] offset:3072 nt
	s_add_i32 s58, s58, s38
	s_lshl_b32 s59, s58, 12
	s_add_u32 s56, s48, s59
	s_addc_u32 s57, s49, 0
	v_mov_b32_e32 v6, s66
	v_fmamk_f32 v6, v6, 0x3a800000, v24
	v_rsq_f32_e32 v6, v6
	s_waitcnt vmcnt(28)
	v_lshlrev_b32_e32 v192, 16, v80
	v_and_b32_e32 v193, 0xffff0000, v80
	v_lshlrev_b32_e32 v194, 16, v81
	v_and_b32_e32 v195, 0xffff0000, v81
	v_lshlrev_b32_e32 v196, 16, v82
	v_and_b32_e32 v197, 0xffff0000, v82
	v_lshlrev_b32_e32 v198, 16, v83
	v_and_b32_e32 v199, 0xffff0000, v83
	v_lshlrev_b32_e32 v200, 16, v84
	v_and_b32_e32 v201, 0xffff0000, v84
	v_lshlrev_b32_e32 v202, 16, v85
	v_and_b32_e32 v203, 0xffff0000, v85
	v_lshlrev_b32_e32 v204, 16, v86
	v_and_b32_e32 v205, 0xffff0000, v86
	v_lshlrev_b32_e32 v206, 16, v87
	v_and_b32_e32 v207, 0xffff0000, v87
	v_pk_mul_f32 v[192:193], v[6:7], v[192:193] op_sel_hi:[0,1]
	v_pk_mul_f32 v[194:195], v[6:7], v[194:195] op_sel_hi:[0,1]
	v_pk_mul_f32 v[196:197], v[6:7], v[196:197] op_sel_hi:[0,1]
	v_pk_mul_f32 v[198:199], v[6:7], v[198:199] op_sel_hi:[0,1]
	v_pk_mul_f32 v[200:201], v[6:7], v[200:201] op_sel_hi:[0,1]
	v_pk_mul_f32 v[202:203], v[6:7], v[202:203] op_sel_hi:[0,1]
	v_pk_mul_f32 v[204:205], v[6:7], v[204:205] op_sel_hi:[0,1]
	v_pk_mul_f32 v[206:207], v[6:7], v[206:207] op_sel_hi:[0,1]
	v_pk_mul_f32 v[192:193], v[8:9], v[192:193]
	v_pk_mul_f32 v[194:195], v[10:11], v[194:195]
	v_pk_mul_f32 v[196:197], v[12:13], v[196:197]
	v_pk_mul_f32 v[198:199], v[14:15], v[198:199]
	v_pk_mul_f32 v[200:201], v[16:17], v[200:201]
	v_pk_mul_f32 v[202:203], v[18:19], v[202:203]
	v_pk_mul_f32 v[204:205], v[20:21], v[204:205]
	v_pk_mul_f32 v[206:207], v[22:23], v[206:207]
	global_store_dwordx4 v4, v[192:195], s[56:57] nt
	global_store_dwordx4 v4, v[196:199], s[56:57] offset:1024 nt
	global_store_dwordx4 v4, v[200:203], s[56:57] offset:2048 nt
	global_store_dwordx4 v4, v[204:207], s[56:57] offset:3072 nt
	s_add_i32 s58, s58, s38
	s_lshl_b32 s59, s58, 12
	s_add_u32 s56, s48, s59
	s_addc_u32 s57, s49, 0
	v_mov_b32_e32 v6, s67
	v_fmamk_f32 v6, v6, 0x3a800000, v24
	v_rsq_f32_e32 v6, v6
	s_waitcnt vmcnt(28)
	v_lshlrev_b32_e32 v208, 16, v88
	v_and_b32_e32 v209, 0xffff0000, v88
	v_lshlrev_b32_e32 v210, 16, v89
	v_and_b32_e32 v211, 0xffff0000, v89
	v_lshlrev_b32_e32 v212, 16, v90
	v_and_b32_e32 v213, 0xffff0000, v90
	v_lshlrev_b32_e32 v214, 16, v91
	v_and_b32_e32 v215, 0xffff0000, v91
	v_lshlrev_b32_e32 v216, 16, v92
	v_and_b32_e32 v217, 0xffff0000, v92
	v_lshlrev_b32_e32 v218, 16, v93
	v_and_b32_e32 v219, 0xffff0000, v93
	v_lshlrev_b32_e32 v220, 16, v94
	v_and_b32_e32 v221, 0xffff0000, v94
	v_lshlrev_b32_e32 v222, 16, v95
	v_and_b32_e32 v223, 0xffff0000, v95
	v_pk_mul_f32 v[208:209], v[6:7], v[208:209] op_sel_hi:[0,1]
	v_pk_mul_f32 v[210:211], v[6:7], v[210:211] op_sel_hi:[0,1]
	v_pk_mul_f32 v[212:213], v[6:7], v[212:213] op_sel_hi:[0,1]
	v_pk_mul_f32 v[214:215], v[6:7], v[214:215] op_sel_hi:[0,1]
	v_pk_mul_f32 v[216:217], v[6:7], v[216:217] op_sel_hi:[0,1]
	v_pk_mul_f32 v[218:219], v[6:7], v[218:219] op_sel_hi:[0,1]
	v_pk_mul_f32 v[220:221], v[6:7], v[220:221] op_sel_hi:[0,1]
	v_pk_mul_f32 v[222:223], v[6:7], v[222:223] op_sel_hi:[0,1]
	v_pk_mul_f32 v[208:209], v[8:9], v[208:209]
	v_pk_mul_f32 v[210:211], v[10:11], v[210:211]
	v_pk_mul_f32 v[212:213], v[12:13], v[212:213]
	v_pk_mul_f32 v[214:215], v[14:15], v[214:215]
	v_pk_mul_f32 v[216:217], v[16:17], v[216:217]
	v_pk_mul_f32 v[218:219], v[18:19], v[218:219]
	v_pk_mul_f32 v[220:221], v[20:21], v[220:221]
	v_pk_mul_f32 v[222:223], v[22:23], v[222:223]
	global_store_dwordx4 v4, v[208:211], s[56:57] nt
	global_store_dwordx4 v4, v[212:215], s[56:57] offset:1024 nt
	global_store_dwordx4 v4, v[216:219], s[56:57] offset:2048 nt
	global_store_dwordx4 v4, v[220:223], s[56:57] offset:3072 nt
	s_lshl_b32 s15, s38, 3
	s_add_i32 s14, s14, s15
	s_branch .Lfn_loop
.Lfn_try4:
	s_mul_i32 s15, s38, 3
	s_add_i32 s15, s15, s14
	s_cmpk_lt_i32 s15, 0x4200
	s_cbranch_scc0 .Lfn_one
	s_mov_b32 s58, s14
	s_lshl_b32 s59, s58, 11
	s_add_u32 s56, s46, s59
	s_addc_u32 s57, s47, 0
	s_lshl_b32 s59, s58, 2
	s_load_dword s60, s[52:53], s59
	global_load_dwordx2 v[32:33], v5, s[56:57]
	global_load_dwordx2 v[34:35], v5, s[56:57] offset:512
	global_load_dwordx2 v[36:37], v5, s[56:57] offset:1024
	global_load_dwordx2 v[38:39], v5, s[56:57] offset:1536
	s_add_i32 s58, s58, s38
	s_lshl_b32 s59, s58, 11
	s_add_u32 s56, s46, s59
	s_addc_u32 s57, s47, 0
	s_lshl_b32 s59, s58, 2
	s_load_dword s61, s[52:53], s59
	global_load_dwordx2 v[40:41], v5, s[56:57]
	global_load_dwordx2 v[42:43], v5, s[56:57] offset:512
	global_load_dwordx2 v[44:45], v5, s[56:57] offset:1024
	global_load_dwordx2 v[46:47], v5, s[56:57] offset:1536
	s_add_i32 s58, s58, s38
	s_lshl_b32 s59, s58, 11
	s_add_u32 s56, s46, s59
	s_addc_u32 s57, s47, 0
	s_lshl_b32 s59, s58, 2
	s_load_dword s62, s[52:53], s59
	global_load_dwordx2 v[48:49], v5, s[56:57]
	global_load_dwordx2 v[50:51], v5, s[56:57] offset:512
	global_load_dwordx2 v[52:53], v5, s[56:57] offset:1024
	global_load_dwordx2 v[54:55], v5, s[56:57] offset:1536
	s_add_i32 s58, s58, s38
	s_lshl_b32 s59, s58, 11
	s_add_u32 s56, s46, s59
	s_addc_u32 s57, s47, 0
	s_lshl_b32 s59, s58, 2
	s_load_dword s63, s[52:53], s59
	global_load_dwordx2 v[56:57], v5, s[56:57]
	global_load_dwordx2 v[58:59], v5, s[56:57] offset:512
	global_load_dwordx2 v[60:61], v5, s[56:57] offset:1024
	global_load_dwordx2 v[62:63], v5, s[56:57] offset:1536
	s_waitcnt lgkmcnt(0)
	s_mov_b32 s58, s14
	s_lshl_b32 s59, s58, 12
	s_add_u32 s56, s48, s59
	s_addc_u32 s57, s49, 0
	v_mov_b32_e32 v6, s60
	v_fmamk_f32 v6, v6, 0x3a800000, v24
	v_rsq_f32_e32 v6, v6
	s_waitcnt vmcnt(12)
	v_lshlrev_b32_e32 v96, 16, v32
	v_and_b32_e32 v97, 0xffff0000, v32
	v_lshlrev_b32_e32 v98, 16, v33
	v_and_b32_e32 v99, 0xffff0000, v33
	v_lshlrev_b32_e32 v100, 16, v34
	v_and_b32_e32 v101, 0xffff0000, v34
	v_lshlrev_b32_e32 v102, 16, v35
	v_and_b32_e32 v103, 0xffff0000, v35
	v_lshlrev_b32_e32 v104, 16, v36
	v_and_b32_e32 v105, 0xffff0000, v36
	v_lshlrev_b32_e32 v106, 16, v37
	v_and_b32_e32 v107, 0xffff0000, v37
	v_lshlrev_b32_e32 v108, 16, v38
	v_and_b32_e32 v109, 0xffff0000, v38
	v_lshlrev_b32_e32 v110, 16, v39
	v_and_b32_e32 v111, 0xffff0000, v39
	v_pk_mul_f32 v[96:97], v[6:7], v[96:97] op_sel_hi:[0,1]
	v_pk_mul_f32 v[98:99], v[6:7], v[98:99] op_sel_hi:[0,1]
	v_pk_mul_f32 v[100:101], v[6:7], v[100:101] op_sel_hi:[0,1]
	v_pk_mul_f32 v[102:103], v[6:7], v[102:103] op_sel_hi:[0,1]
	v_pk_mul_f32 v[104:105], v[6:7], v[104:105] op_sel_hi:[0,1]
	v_pk_mul_f32 v[106:107], v[6:7], v[106:107] op_sel_hi:[0,1]
	v_pk_mul_f32 v[108:109], v[6:7], v[108:109] op_sel_hi:[0,1]
	v_pk_mul_f32 v[110:111], v[6:7], v[110:111] op_sel_hi:[0,1]
	v_pk_mul_f32 v[96:97], v[8:9], v[96:97]
	v_pk_mul_f32 v[98:99], v[10:11], v[98:99]
	v_pk_mul_f32 v[100:101], v[12:13], v[100:101]
	v_pk_mul_f32 v[102:103], v[14:15], v[102:103]
	v_pk_mul_f32 v[104:105], v[16:17], v[104:105]
	v_pk_mul_f32 v[106:107], v[18:19], v[106:107]
	v_pk_mul_f32 v[108:109], v[20:21], v[108:109]
	v_pk_mul_f32 v[110:111], v[22:23], v[110:111]
	global_store_dwordx4 v4, v[96:99], s[56:57] nt
	global_store_dwordx4 v4, v[100:103], s[56:57] offset:1024 nt
	global_store_dwordx4 v4, v[104:107], s[56:57] offset:2048 nt
	global_store_dwordx4 v4, v[108:111], s[56:57] offset:3072 nt
	s_add_i32 s58, s58, s38
	s_lshl_b32 s59, s58, 12
	s_add_u32 s56, s48, s59
	s_addc_u32 s57, s49, 0
	v_mov_b32_e32 v6, s61
	v_fmamk_f32 v6, v6, 0x3a800000, v24
	v_rsq_f32_e32 v6, v6
	s_waitcnt vmcnt(12)
	v_lshlrev_b32_e32 v112, 16, v40
	v_and_b32_e32 v113, 0xffff0000, v40
	v_lshlrev_b32_e32 v114, 16, v41
	v_and_b32_e32 v115, 0xffff0000, v41
	v_lshlrev_b32_e32 v116, 16, v42
	v_and_b32_e32 v117, 0xffff0000, v42
	v_lshlrev_b32_e32 v118, 16, v43
	v_and_b32_e32 v119, 0xffff0000, v43
	v_lshlrev_b32_e32 v120, 16, v44
	v_and_b32_e32 v121, 0xffff0000, v44
	v_lshlrev_b32_e32 v122, 16, v45
	v_and_b32_e32 v123, 0xffff0000, v45
	v_lshlrev_b32_e32 v124, 16, v46
	v_and_b32_e32 v125, 0xffff0000, v46
	v_lshlrev_b32_e32 v126, 16, v47
	v_and_b32_e32 v127, 0xffff0000, v47
	v_pk_mul_f32 v[112:113], v[6:7], v[112:113] op_sel_hi:[0,1]
	v_pk_mul_f32 v[114:115], v[6:7], v[114:115] op_sel_hi:[0,1]
	v_pk_mul_f32 v[116:117], v[6:7], v[116:117] op_sel_hi:[0,1]
	v_pk_mul_f32 v[118:119], v[6:7], v[118:119] op_sel_hi:[0,1]
	v_pk_mul_f32 v[120:121], v[6:7], v[120:121] op_sel_hi:[0,1]
	v_pk_mul_f32 v[122:123], v[6:7], v[122:123] op_sel_hi:[0,1]
	v_pk_mul_f32 v[124:125], v[6:7], v[124:125] op_sel_hi:[0,1]
	v_pk_mul_f32 v[126:127], v[6:7], v[126:127] op_sel_hi:[0,1]
	v_pk_mul_f32 v[112:113], v[8:9], v[112:113]
	v_pk_mul_f32 v[114:115], v[10:11], v[114:115]
	v_pk_mul_f32 v[116:117], v[12:13], v[116:117]
	v_pk_mul_f32 v[118:119], v[14:15], v[118:119]
	v_pk_mul_f32 v[120:121], v[16:17], v[120:121]
	v_pk_mul_f32 v[122:123], v[18:19], v[122:123]
	v_pk_mul_f32 v[124:125], v[20:21], v[124:125]
	v_pk_mul_f32 v[126:127], v[22:23], v[126:127]
	global_store_dwordx4 v4, v[112:115], s[56:57] nt
	global_store_dwordx4 v4, v[116:119], s[56:57] offset:1024 nt
	global_store_dwordx4 v4, v[120:123], s[56:57] offset:2048 nt
	global_store_dwordx4 v4, v[124:127], s[56:57] offset:3072 nt
	s_add_i32 s58, s58, s38
	s_lshl_b32 s59, s58, 12
	s_add_u32 s56, s48, s59
	s_addc_u32 s57, s49, 0
	v_mov_b32_e32 v6, s62
	v_fmamk_f32 v6, v6, 0x3a800000, v24
	v_rsq_f32_e32 v6, v6
	s_waitcnt vmcnt(12)
	v_lshlrev_b32_e32 v128, 16, v48
	v_and_b32_e32 v129, 0xffff0000, v48
	v_lshlrev_b32_e32 v130, 16, v49
	v_and_b32_e32 v131, 0xffff0000, v49
	v_lshlrev_b32_e32 v132, 16, v50
	v_and_b32_e32 v133, 0xffff0000, v50
	v_lshlrev_b32_e32 v134, 16, v51
	v_and_b32_e32 v135, 0xffff0000, v51
	v_lshlrev_b32_e32 v136, 16, v52
	v_and_b32_e32 v137, 0xffff0000, v52
	v_lshlrev_b32_e32 v138, 16, v53
	v_and_b32_e32 v139, 0xffff0000, v53
	v_lshlrev_b32_e32 v140, 16, v54
	v_and_b32_e32 v141, 0xffff0000, v54
	v_lshlrev_b32_e32 v142, 16, v55
	v_and_b32_e32 v143, 0xffff0000, v55
	v_pk_mul_f32 v[128:129], v[6:7], v[128:129] op_sel_hi:[0,1]
	v_pk_mul_f32 v[130:131], v[6:7], v[130:131] op_sel_hi:[0,1]
	v_pk_mul_f32 v[132:133], v[6:7], v[132:133] op_sel_hi:[0,1]
	v_pk_mul_f32 v[134:135], v[6:7], v[134:135] op_sel_hi:[0,1]
	v_pk_mul_f32 v[136:137], v[6:7], v[136:137] op_sel_hi:[0,1]
	v_pk_mul_f32 v[138:139], v[6:7], v[138:139] op_sel_hi:[0,1]
	v_pk_mul_f32 v[140:141], v[6:7], v[140:141] op_sel_hi:[0,1]
	v_pk_mul_f32 v[142:143], v[6:7], v[142:143] op_sel_hi:[0,1]
	v_pk_mul_f32 v[128:129], v[8:9], v[128:129]
	v_pk_mul_f32 v[130:131], v[10:11], v[130:131]
	v_pk_mul_f32 v[132:133], v[12:13], v[132:133]
	v_pk_mul_f32 v[134:135], v[14:15], v[134:135]
	v_pk_mul_f32 v[136:137], v[16:17], v[136:137]
	v_pk_mul_f32 v[138:139], v[18:19], v[138:139]
	v_pk_mul_f32 v[140:141], v[20:21], v[140:141]
	v_pk_mul_f32 v[142:143], v[22:23], v[142:143]
	global_store_dwordx4 v4, v[128:131], s[56:57] nt
	global_store_dwordx4 v4, v[132:135], s[56:57] offset:1024 nt
	global_store_dwordx4 v4, v[136:139], s[56:57] offset:2048 nt
	global_store_dwordx4 v4, v[140:143], s[56:57] offset:3072 nt
	s_add_i32 s58, s58, s38
	s_lshl_b32 s59, s58, 12
	s_add_u32 s56, s48, s59
	s_addc_u32 s57, s49, 0
	v_mov_b32_e32 v6, s63
	v_fmamk_f32 v6, v6, 0x3a800000, v24
	v_rsq_f32_e32 v6, v6
	s_waitcnt vmcnt(12)
	v_lshlrev_b32_e32 v144, 16, v56
	v_and_b32_e32 v145, 0xffff0000, v56
	v_lshlrev_b32_e32 v146, 16, v57
	v_and_b32_e32 v147, 0xffff0000, v57
	v_lshlrev_b32_e32 v148, 16, v58
	v_and_b32_e32 v149, 0xffff0000, v58
	v_lshlrev_b32_e32 v150, 16, v59
	v_and_b32_e32 v151, 0xffff0000, v59
	v_lshlrev_b32_e32 v152, 16, v60
	v_and_b32_e32 v153, 0xffff0000, v60
	v_lshlrev_b32_e32 v154, 16, v61
	v_and_b32_e32 v155, 0xffff0000, v61
	v_lshlrev_b32_e32 v156, 16, v62
	v_and_b32_e32 v157, 0xffff0000, v62
	v_lshlrev_b32_e32 v158, 16, v63
	v_and_b32_e32 v159, 0xffff0000, v63
	v_pk_mul_f32 v[144:145], v[6:7], v[144:145] op_sel_hi:[0,1]
	v_pk_mul_f32 v[146:147], v[6:7], v[146:147] op_sel_hi:[0,1]
	v_pk_mul_f32 v[148:149], v[6:7], v[148:149] op_sel_hi:[0,1]
	v_pk_mul_f32 v[150:151], v[6:7], v[150:151] op_sel_hi:[0,1]
	v_pk_mul_f32 v[152:153], v[6:7], v[152:153] op_sel_hi:[0,1]
	v_pk_mul_f32 v[154:155], v[6:7], v[154:155] op_sel_hi:[0,1]
	v_pk_mul_f32 v[156:157], v[6:7], v[156:157] op_sel_hi:[0,1]
	v_pk_mul_f32 v[158:159], v[6:7], v[158:159] op_sel_hi:[0,1]
	v_pk_mul_f32 v[144:145], v[8:9], v[144:145]
	v_pk_mul_f32 v[146:147], v[10:11], v[146:147]
	v_pk_mul_f32 v[148:149], v[12:13], v[148:149]
	v_pk_mul_f32 v[150:151], v[14:15], v[150:151]
	v_pk_mul_f32 v[152:153], v[16:17], v[152:153]
	v_pk_mul_f32 v[154:155], v[18:19], v[154:155]
	v_pk_mul_f32 v[156:157], v[20:21], v[156:157]
	v_pk_mul_f32 v[158:159], v[22:23], v[158:159]
	global_store_dwordx4 v4, v[144:147], s[56:57] nt
	global_store_dwordx4 v4, v[148:151], s[56:57] offset:1024 nt
	global_store_dwordx4 v4, v[152:155], s[56:57] offset:2048 nt
	global_store_dwordx4 v4, v[156:159], s[56:57] offset:3072 nt
	s_lshl_b32 s15, s38, 2
	s_add_i32 s14, s14, s15
	s_branch .Lfn_loop
.Lfn_one:
	s_mov_b32 s58, s14
	s_lshl_b32 s59, s58, 11
	s_add_u32 s56, s46, s59
	s_addc_u32 s57, s47, 0
	s_lshl_b32 s59, s58, 2
	s_load_dword s60, s[52:53], s59
	global_load_dwordx2 v[32:33], v5, s[56:57]
	global_load_dwordx2 v[34:35], v5, s[56:57] offset:512
	global_load_dwordx2 v[36:37], v5, s[56:57] offset:1024
	global_load_dwordx2 v[38:39], v5, s[56:57] offset:1536
	s_waitcnt lgkmcnt(0)
	s_mov_b32 s58, s14
	s_lshl_b32 s59, s58, 12
	s_add_u32 s56, s48, s59
	s_addc_u32 s57, s49, 0
	v_mov_b32_e32 v6, s60
	v_fmamk_f32 v6, v6, 0x3a800000, v24
	v_rsq_f32_e32 v6, v6
	s_waitcnt vmcnt(0)
	v_lshlrev_b32_e32 v96, 16, v32
	v_and_b32_e32 v97, 0xffff0000, v32
	v_lshlrev_b32_e32 v98, 16, v33
	v_and_b32_e32 v99, 0xffff0000, v33
	v_lshlrev_b32_e32 v100, 16, v34
	v_and_b32_e32 v101, 0xffff0000, v34
	v_lshlrev_b32_e32 v102, 16, v35
	v_and_b32_e32 v103, 0xffff0000, v35
	v_lshlrev_b32_e32 v104, 16, v36
	v_and_b32_e32 v105, 0xffff0000, v36
	v_lshlrev_b32_e32 v106, 16, v37
	v_and_b32_e32 v107, 0xffff0000, v37
	v_lshlrev_b32_e32 v108, 16, v38
	v_and_b32_e32 v109, 0xffff0000, v38
	v_lshlrev_b32_e32 v110, 16, v39
	v_and_b32_e32 v111, 0xffff0000, v39
	v_pk_mul_f32 v[96:97], v[6:7], v[96:97] op_sel_hi:[0,1]
	v_pk_mul_f32 v[98:99], v[6:7], v[98:99] op_sel_hi:[0,1]
	v_pk_mul_f32 v[100:101], v[6:7], v[100:101] op_sel_hi:[0,1]
	v_pk_mul_f32 v[102:103], v[6:7], v[102:103] op_sel_hi:[0,1]
	v_pk_mul_f32 v[104:105], v[6:7], v[104:105] op_sel_hi:[0,1]
	v_pk_mul_f32 v[106:107], v[6:7], v[106:107] op_sel_hi:[0,1]
	v_pk_mul_f32 v[108:109], v[6:7], v[108:109] op_sel_hi:[0,1]
	v_pk_mul_f32 v[110:111], v[6:7], v[110:111] op_sel_hi:[0,1]
	v_pk_mul_f32 v[96:97], v[8:9], v[96:97]
	v_pk_mul_f32 v[98:99], v[10:11], v[98:99]
	v_pk_mul_f32 v[100:101], v[12:13], v[100:101]
	v_pk_mul_f32 v[102:103], v[14:15], v[102:103]
	v_pk_mul_f32 v[104:105], v[16:17], v[104:105]
	v_pk_mul_f32 v[106:107], v[18:19], v[106:107]
	v_pk_mul_f32 v[108:109], v[20:21], v[108:109]
	v_pk_mul_f32 v[110:111], v[22:23], v[110:111]
	global_store_dwordx4 v4, v[96:99], s[56:57] nt
	global_store_dwordx4 v4, v[100:103], s[56:57] offset:1024 nt
	global_store_dwordx4 v4, v[104:107], s[56:57] offset:2048 nt
	global_store_dwordx4 v4, v[108:111], s[56:57] offset:3072 nt
	s_add_i32 s14, s14, s38
	s_branch .Lfn_loop
